# v19 + P0 table work (SSM tables, pos-embed, W_s cast) assigned to blocks in reverse order so the GEMV blocks are not also the table-heavy blocks
# speedup vs baseline: 1.0031x; 1.0031x over previous
.LBB0_31:
	s_sub_u32 s32, 0xff, s2
	v_lshl_add_u32 v6, s32, 9, v190
	s_movk_i32 s0, 0x2000
	s_lshl_b32 s18, s33, 9
	v_cmp_gt_i32_e32 vcc, s0, v6
	v_ashrrev_i32_e32 v7, 31, v6
	s_and_saveexec_b64 s[8:9], vcc
	s_cbranch_execz .LBB0_38
	v_lshl_add_u64 v[2:3], v[6:7], 3, s[62:63]
	s_mov_b64 s[0:1], 0x100000
	s_ashr_i32 s19, s18, 31
	v_lshl_add_u64 v[2:3], v[2:3], 0, s[0:1]
	s_lshl_b64 s[10:11], s[18:19], 3
	s_mov_b64 s[12:13], 0
	s_mov_b32 s16, 0x3fb8aa3b
	s_mov_b32 s17, 0xc2ce8ed0
	s_mov_b32 s19, 0x42b17218
	v_mov_b32_e32 v1, 0x7f800000
	v_mov_b32_e32 v5, 0
	s_mov_b32 s20, 0x4e441529
	s_mov_b32 s21, 0xa2f9836e
	s_mov_b32 s22, 0x3fc90fda
	s_mov_b32 s23, 0x3f22f983
	s_mov_b32 s24, 0xbfc90fda
	v_mov_b32_e32 v8, 0x3c0881c4
	v_mov_b32_e32 v9, 0xbab64f3b
	s_brev_b32 s25, 1
	s_movk_i32 s27, 0x1f8
	s_movk_i32 s28, 0x1fff
	v_not_b32_e32 v10, 63
	v_not_b32_e32 v11, 31
	v_mov_b32_e32 v12, 0x7fc00000
	v_mov_b32_e32 v13, v6
	s_branch .LBB0_34

.LBB0_47:
	s_or_b64 exec, exec, s[10:11]
	s_mov_b32 s0, 0x8000
	v_cmp_gt_i32_e32 vcc, s0, v6
	s_and_saveexec_b64 s[0:1], vcc
	v_readlane_b32 s64, v254, 22
	v_readlane_b32 s66, v254, 24
	v_readlane_b32 s67, v254, 25
	v_readlane_b32 s68, v254, 26
	v_readlane_b32 s69, v254, 27
	v_readlane_b32 s65, v254, 23
	v_readlane_b32 s70, v254, 28
	v_readlane_b32 s71, v254, 29
	v_readlane_b32 s72, v254, 30
	v_readlane_b32 s73, v254, 31
	v_readlane_b32 s74, v254, 32
	v_readlane_b32 s75, v254, 33
	v_readlane_b32 s76, v254, 34
	v_readlane_b32 s77, v254, 35
	v_readlane_b32 s78, v254, 36
	v_readlane_b32 s79, v254, 37
	s_cbranch_execz .LBB0_50
	v_lshl_add_u64 v[2:3], v[6:7], 4, s[62:63]
	s_mov_b64 s[4:5], 0x300000
	s_ashr_i32 s19, s18, 31
	v_lshlrev_b32_e32 v1, 6, v190
	v_lshl_add_u64 v[2:3], v[2:3], 0, s[4:5]
	s_lshl_b64 s[4:5], s[18:19], 4
	v_lshl_add_u32 v1, s32, 15, v1
	s_lshl_b32 s8, s33, 15
	s_mov_b64 s[6:7], 0
	s_movk_i32 s9, 0xffc0
	v_mov_b32_e32 v5, 0
	s_movk_i32 s10, 0x7fff
	v_mov_b32_e32 v8, v6
